# SwiGLU epilogue: rsq results written directly to consumer registers (eight v_mov copies and one s_nop removed per unit)
# speedup vs baseline: 1.0010x; 1.0010x over previous
; __device__ __forceinline__ unsigned cvtpk(float lo, float hi) { f32x2_t v = {lo, hi}; bf16x2_t b = __builtin_convertvector(v, bf16x2_t); return __builtin_bit_cast(unsigned, b); }
; #define WAIT8(a) asm volatile("s_waitcnt vmcnt(0)" : "+v"(a[0]), "+v"(a[1]), "+v"(a[2]), "+v"(a[3]), "+v"(a[4]), "+v"(a[5]), "+v"(a[6]), "+v"(a[7]) :: "memory")
; __device__ __forceinline__ void rows_rstd_finish(f32x4 (&p)[8], float (&rs)[2][4]) {
;     WAIT8(p);
; #pragma unroll
;     for (int i = 0; i < 8; ++i) {
;         float s = (p[i].x + p[i].y) + (p[i].z + p[i].w);
;         s += __shfl_xor(s, 16); s += __shfl_xor(s, 32);
;         rs[i >> 2][i & 3] = __builtin_amdgcn_rsqf(s * (1.f / D) + EPS);
;     }
;     __device__ __forceinline__ void operator()(const AccT& acc, const Unit& u, int wr, int wc, int fr, int fq, LAS unsigned char* stg) const {
;         const int row0 = u.pm * BM + wr * 64 + fr;
;         float rs[2][4];
;         rows_rstd(SS, row0, fq, rs);
; #pragma unroll
;         for (int ai = 0; ai < 2; ++ai)
; #pragma unroll
;             for (int m = 0; m < 4; ++m) {
;                 bf16_t* rowp = O + ((size_t)(u.pm * 16 + wr * 4 + ai * 8 + m) * (ldo >> 5) + (u.pn * 4 + wc)) * 512 + fr * 32 + 8 * fq;
;                 const float k1 = rs[ai][m] * -1.4426950408889634f, k2 = rs[ai][m] * rs[ai][m];
;                 float r[8];
; #pragma unroll
;                 for (int n = 0; n < 2; ++n)
; #pragma unroll
;                     for (int i = 0; i < 4; ++i) {
;                         const float g = acc[ai][0][m][n][i], up = acc[ai][1][m][n][i];
;                         const float e = __builtin_amdgcn_exp2f(g * k1);
;                         r[n * 4 + i] = (g * up) * (k2 * __builtin_amdgcn_rcpf(1.0f + e));
;                     }
;                 u32x4 w; w.x = cvtpk(r[0], r[1]); w.y = cvtpk(r[2], r[3]); w.z = cvtpk(r[4], r[5]); w.w = cvtpk(r[6], r[7]);
;                 __builtin_nontemporal_store(w, (u32x4*)rowp);
;             }
.LBB0_456:
	v_and_b32_e32 v145, 48, v223
	v_lshl_add_u32 v145, v142, 6, v145
	v_add_u32_e32 v145, 0x20800, v145
	ds_read_b128 v[146:149], v145
	ds_read_b128 v[150:153], v145 offset:1024
	ds_read_b128 v[154:157], v145 offset:2048
	ds_read_b128 v[158:161], v145 offset:3072
	ds_read_b128 v[162:165], v145 offset:8192
	ds_read_b128 v[166:169], v145 offset:9216
	ds_read_b128 v[170:173], v145 offset:10240
	ds_read_b128 v[194:197], v145 offset:11264
	v_pk_mul_f32 v[122:123], v[126:127], v[122:123]
	v_pk_mul_f32 v[120:121], v[124:125], v[120:121]
	v_pk_mul_f32 v[114:115], v[118:119], v[114:115]
	s_waitcnt lgkmcnt(0)
	v_add_f32_e32 v146, v146, v147
	v_add_f32_e32 v150, v150, v151
	v_add_f32_e32 v154, v154, v155
	v_add_f32_e32 v158, v158, v159
	v_add_f32_e32 v162, v162, v163
	v_add_f32_e32 v166, v166, v167
	v_add_f32_e32 v170, v170, v171
	v_add_f32_e32 v194, v194, v195
	v_add_f32_e32 v148, v148, v149
	v_add_f32_e32 v152, v152, v153
	v_add_f32_e32 v156, v156, v157
	v_add_f32_e32 v160, v160, v161
	v_add_f32_e32 v164, v164, v165
	v_add_f32_e32 v168, v168, v169
	v_add_f32_e32 v172, v172, v173
	v_add_f32_e32 v196, v196, v197
	v_add_f32_e32 v146, v146, v148
	v_add_f32_e32 v150, v150, v152
	v_add_f32_e32 v154, v154, v156
	v_add_f32_e32 v158, v158, v160
	v_add_f32_e32 v162, v162, v164
	v_add_f32_e32 v166, v166, v168
	v_add_f32_e32 v170, v170, v172
	v_add_f32_e32 v194, v194, v196
	v_mov_b32_e32 v147, v146
	v_mov_b32_e32 v151, v150
	v_mov_b32_e32 v155, v154
	v_mov_b32_e32 v159, v158
	v_mov_b32_e32 v163, v162
	v_mov_b32_e32 v167, v166
	v_mov_b32_e32 v171, v170
	v_mov_b32_e32 v195, v194
	s_nop 0
	v_permlane16_swap_b32_e32 v146, v147
	v_permlane16_swap_b32_e32 v150, v151
	v_permlane16_swap_b32_e32 v154, v155
	v_permlane16_swap_b32_e32 v158, v159
	v_permlane16_swap_b32_e32 v162, v163
	v_permlane16_swap_b32_e32 v166, v167
	v_permlane16_swap_b32_e32 v170, v171
	v_permlane16_swap_b32_e32 v194, v195
	s_nop 0
	v_add_f32_e32 v146, v146, v147
	v_add_f32_e32 v150, v150, v151
	v_add_f32_e32 v154, v154, v155
	v_add_f32_e32 v158, v158, v159
	v_add_f32_e32 v162, v162, v163
	v_add_f32_e32 v166, v166, v167
	v_add_f32_e32 v170, v170, v171
	v_add_f32_e32 v194, v194, v195
	v_mov_b32_e32 v147, v146
	v_mov_b32_e32 v151, v150
	v_mov_b32_e32 v155, v154
	v_mov_b32_e32 v159, v158
	v_mov_b32_e32 v163, v162
	v_mov_b32_e32 v167, v166
	v_mov_b32_e32 v171, v170
	v_mov_b32_e32 v195, v194
	s_nop 0
	v_permlane32_swap_b32_e32 v146, v147
	v_permlane32_swap_b32_e32 v150, v151
	v_permlane32_swap_b32_e32 v154, v155
	v_permlane32_swap_b32_e32 v158, v159
	v_permlane32_swap_b32_e32 v162, v163
	v_permlane32_swap_b32_e32 v166, v167
	v_permlane32_swap_b32_e32 v170, v171
	v_permlane32_swap_b32_e32 v194, v195
	s_nop 0
	v_add_f32_e32 v146, v146, v147
	v_add_f32_e32 v150, v150, v151
	v_add_f32_e32 v154, v154, v155
	v_add_f32_e32 v158, v158, v159
	v_add_f32_e32 v162, v162, v163
	v_add_f32_e32 v166, v166, v167
	v_add_f32_e32 v170, v170, v171
	v_add_f32_e32 v194, v194, v195
	v_fmamk_f32 v146, v146, 0x3a800000, v220
	v_fmamk_f32 v150, v150, 0x3a800000, v220
	v_fmamk_f32 v154, v154, 0x3a800000, v220
	v_fmamk_f32 v158, v158, 0x3a800000, v220
	v_fmamk_f32 v162, v162, 0x3a800000, v220
	v_fmamk_f32 v166, v166, 0x3a800000, v220
	v_fmamk_f32 v170, v170, 0x3a800000, v220
	v_fmamk_f32 v194, v194, 0x3a800000, v220
	v_rsq_f32_e32 v149, v146
	v_rsq_f32_e32 v153, v154
	v_rsq_f32_e32 v154, v150
	v_rsq_f32_e32 v155, v158
	v_rsq_f32_e32 v152, v162
	v_rsq_f32_e32 v147, v166
	v_rsq_f32_e32 v146, v170
	v_rsq_f32_e32 v145, v194
	s_lshl_b32 s11, s50, 4
	s_lshl_b32 s2, s49, 2
	s_add_i32 s11, s11, s47
	s_or_b32 s2, s2, s44
	s_ashr_i32 s3, s2, 31
	s_mul_i32 s13, s11, 0x58
	v_mul_f32_e32 v156, 0xbfb8aa3b, v149
	v_mul_f32_e32 v157, v127, v156
	v_exp_f32_e32 v157, v157
	v_mul_f32_e32 v148, v124, v156
	v_exp_f32_e32 v150, v148
	v_mul_f32_e32 v148, v125, v156
	v_exp_f32_e32 v151, v148
	v_mul_f32_e32 v148, v149, v149
	v_add_f32_e32 v149, 1.0, v150
	v_rcp_f32_e32 v150, v149
	v_add_f32_e32 v149, 1.0, v151
	v_rcp_f32_e32 v151, v149
	v_mul_f32_e32 v149, v126, v156
	v_exp_f32_e32 v149, v149
	v_add_f32_e32 v127, 1.0, v157
	v_rcp_f32_e32 v127, v127
	s_mul_hi_i32 s29, s11, 0x58
	v_add_f32_e32 v126, 1.0, v149
	v_rcp_f32_e32 v126, v126
	v_pk_mul_f32 v[124:125], v[148:149], v[150:151] op_sel_hi:[0,1]
	v_pk_mul_f32 v[120:121], v[120:121], v[124:125]
	s_add_u32 s28, s13, s2
	v_pk_mul_f32 v[124:125], v[148:149], v[126:127] op_sel_hi:[0,1]
	v_mul_f32_e32 v126, v116, v156
	v_mul_f32_e32 v127, v117, v156
	v_exp_f32_e32 v126, v126
	v_exp_f32_e32 v127, v127
	v_pk_mul_f32 v[122:123], v[122:123], v[124:125]
	v_pk_mul_f32 v[112:113], v[116:117], v[112:113]
	v_add_f32_e32 v124, 1.0, v126
	v_add_f32_e32 v125, 1.0, v127
	v_mul_f32_e32 v126, v118, v156
	v_mul_f32_e32 v127, v119, v156
	v_exp_f32_e32 v126, v126
	v_exp_f32_e32 v127, v127
	v_rcp_f32_e32 v124, v124
	v_rcp_f32_e32 v125, v125
	v_add_f32_e32 v118, 1.0, v126
	v_add_f32_e32 v119, 1.0, v127
	v_rcp_f32_e32 v118, v118
	v_rcp_f32_e32 v119, v119
	v_pk_mul_f32 v[116:117], v[148:149], v[124:125] op_sel_hi:[0,1]
	s_addc_u32 s29, s29, s3
	v_pk_mul_f32 v[116:117], v[112:113], v[116:117]
	v_pk_mul_f32 v[112:113], v[148:149], v[118:119] op_sel_hi:[0,1]
	s_lshl_b64 s[28:29], s[28:29], 10
	v_pk_mul_f32 v[118:119], v[114:115], v[112:113]
	v_lshl_add_u64 v[124:125], v[134:135], 0, s[28:29]
	v_cvt_pk_bf16_f32 v112, v120, v121
	v_cvt_pk_bf16_f32 v113, v122, v123
	v_cvt_pk_bf16_f32 v114, v116, v117
	v_cvt_pk_bf16_f32 v115, v118, v119
	global_store_dwordx4 v[124:125], v[112:115], off nt
	v_pk_mul_f32 v[106:107], v[110:111], v[106:107]
	v_pk_mul_f32 v[104:105], v[108:109], v[104:105]
	v_mul_f32_e32 v113, 0xbfb8aa3b, v154
; __device__ __forceinline__ unsigned cvtpk(float lo, float hi) { f32x2_t v = {lo, hi}; bf16x2_t b = __builtin_convertvector(v, bf16x2_t); return __builtin_bit_cast(unsigned, b); }
;     __device__ __forceinline__ void operator()(const AccT& acc, const Unit& u, int wr, int wc, int fr, int fq, LAS unsigned char* stg) const {
;     ...
;                 const float k1 = rs[ai][m] * -1.4426950408889634f, k2 = rs[ai][m] * rs[ai][m];
;                 float r[8];
; #pragma unroll
;                 for (int n = 0; n < 2; ++n)
; #pragma unroll
;                     for (int i = 0; i < 4; ++i) {
;                         const float g = acc[ai][0][m][n][i], up = acc[ai][1][m][n][i];
;                         const float e = __builtin_amdgcn_exp2f(g * k1);
;                         r[n * 4 + i] = (g * up) * (k2 * __builtin_amdgcn_rcpf(1.0f + e));
;                     }
;                 u32x4 w; w.x = cvtpk(r[0], r[1]); w.y = cvtpk(r[2], r[3]); w.z = cvtpk(r[4], r[5]); w.w = cvtpk(r[6], r[7]);
;                 __builtin_nontemporal_store(w, (u32x4*)rowp);
	v_mul_f32_e32 v112, v108, v113
	v_exp_f32_e32 v114, v112
	v_mul_f32_e32 v112, v109, v113
	v_exp_f32_e32 v115, v112
	v_mul_f32_e32 v116, v110, v113
	v_mul_f32_e32 v117, v111, v113
	v_exp_f32_e32 v116, v116
	v_exp_f32_e32 v117, v117
	v_add_f32_e32 v114, 1.0, v114
	v_add_f32_e32 v115, 1.0, v115
	v_rcp_f32_e32 v114, v114
	v_rcp_f32_e32 v115, v115
	v_add_f32_e32 v110, 1.0, v116
	v_add_f32_e32 v111, 1.0, v117
	v_rcp_f32_e32 v110, v110
	v_rcp_f32_e32 v111, v111
	v_mul_f32_e32 v112, v154, v154
	v_pk_mul_f32 v[108:109], v[112:113], v[114:115] op_sel_hi:[0,1]
	v_pk_mul_f32 v[104:105], v[104:105], v[108:109]
	v_pk_mul_f32 v[108:109], v[112:113], v[110:111] op_sel_hi:[0,1]
	v_mul_f32_e32 v110, v100, v113
	v_mul_f32_e32 v111, v101, v113
	v_exp_f32_e32 v110, v110
	v_exp_f32_e32 v111, v111
	v_pk_mul_f32 v[106:107], v[106:107], v[108:109]
	v_pk_mul_f32 v[98:99], v[102:103], v[98:99]
	v_add_f32_e32 v108, 1.0, v110
	v_add_f32_e32 v109, 1.0, v111
	v_mul_f32_e32 v110, v102, v113
	v_mul_f32_e32 v111, v103, v113
	v_exp_f32_e32 v110, v110
	v_exp_f32_e32 v111, v111
	v_rcp_f32_e32 v108, v108
	v_rcp_f32_e32 v109, v109
	v_add_f32_e32 v102, 1.0, v110
	v_add_f32_e32 v103, 1.0, v111
	v_rcp_f32_e32 v102, v102
	v_rcp_f32_e32 v103, v103
	s_or_b32 s28, s11, 1
	s_mul_hi_i32 s29, s28, 0x58
	s_mulk_i32 s28, 0x58
	s_add_u32 s28, s28, s2
	v_pk_mul_f32 v[96:97], v[100:101], v[96:97]
	v_pk_mul_f32 v[100:101], v[112:113], v[108:109] op_sel_hi:[0,1]
	s_addc_u32 s29, s29, s3
	v_pk_mul_f32 v[100:101], v[96:97], v[100:101]
	v_pk_mul_f32 v[96:97], v[112:113], v[102:103] op_sel_hi:[0,1]
	s_lshl_b64 s[28:29], s[28:29], 10
	v_pk_mul_f32 v[102:103], v[98:99], v[96:97]
	v_lshl_add_u64 v[108:109], v[134:135], 0, s[28:29]
	v_cvt_pk_bf16_f32 v96, v104, v105
	v_cvt_pk_bf16_f32 v97, v106, v107
	v_cvt_pk_bf16_f32 v98, v100, v101
	v_cvt_pk_bf16_f32 v99, v102, v103
	global_store_dwordx4 v[108:109], v[96:99], off nt
	v_pk_mul_f32 v[90:91], v[94:95], v[90:91]
	v_pk_mul_f32 v[88:89], v[92:93], v[88:89]
	v_mul_f32_e32 v97, 0xbfb8aa3b, v153
	v_mul_f32_e32 v96, v92, v97
	v_exp_f32_e32 v98, v96
	v_mul_f32_e32 v96, v93, v97
	v_exp_f32_e32 v99, v96
	v_mul_f32_e32 v100, v94, v97
	v_mul_f32_e32 v101, v95, v97
	v_exp_f32_e32 v100, v100
	v_exp_f32_e32 v101, v101
	v_add_f32_e32 v98, 1.0, v98
	v_add_f32_e32 v99, 1.0, v99
	v_rcp_f32_e32 v98, v98
	v_rcp_f32_e32 v99, v99
	v_add_f32_e32 v94, 1.0, v100
	v_add_f32_e32 v95, 1.0, v101
	v_rcp_f32_e32 v94, v94
	v_rcp_f32_e32 v95, v95
	v_mul_f32_e32 v96, v153, v153
	v_pk_mul_f32 v[92:93], v[96:97], v[98:99] op_sel_hi:[0,1]
	v_pk_mul_f32 v[88:89], v[88:89], v[92:93]
	v_pk_mul_f32 v[92:93], v[96:97], v[94:95] op_sel_hi:[0,1]
	v_mul_f32_e32 v94, v84, v97
	v_mul_f32_e32 v95, v85, v97
	v_exp_f32_e32 v94, v94
	v_exp_f32_e32 v95, v95
	v_pk_mul_f32 v[90:91], v[90:91], v[92:93]
	v_pk_mul_f32 v[82:83], v[86:87], v[82:83]
	v_add_f32_e32 v92, 1.0, v94
	v_add_f32_e32 v93, 1.0, v95
	v_mul_f32_e32 v94, v86, v97
	v_mul_f32_e32 v95, v87, v97
	v_exp_f32_e32 v94, v94
	v_exp_f32_e32 v95, v95
	v_rcp_f32_e32 v92, v92
	v_rcp_f32_e32 v93, v93
	v_add_f32_e32 v86, 1.0, v94
	v_add_f32_e32 v87, 1.0, v95
	v_rcp_f32_e32 v86, v86
	v_rcp_f32_e32 v87, v87
	s_or_b32 s28, s11, 2
	s_mul_hi_i32 s29, s28, 0x58
	s_mulk_i32 s28, 0x58
	s_add_u32 s28, s28, s2
	v_pk_mul_f32 v[80:81], v[84:85], v[80:81]
	v_pk_mul_f32 v[84:85], v[96:97], v[92:93] op_sel_hi:[0,1]
	s_addc_u32 s29, s29, s3
	v_pk_mul_f32 v[84:85], v[80:81], v[84:85]
	v_pk_mul_f32 v[80:81], v[96:97], v[86:87] op_sel_hi:[0,1]
	s_lshl_b64 s[28:29], s[28:29], 10
	v_pk_mul_f32 v[86:87], v[82:83], v[80:81]
	v_lshl_add_u64 v[92:93], v[134:135], 0, s[28:29]
	v_cvt_pk_bf16_f32 v80, v88, v89
	v_cvt_pk_bf16_f32 v81, v90, v91
	v_cvt_pk_bf16_f32 v82, v84, v85
	v_cvt_pk_bf16_f32 v83, v86, v87
	global_store_dwordx4 v[92:93], v[80:83], off nt
	v_pk_mul_f32 v[74:75], v[78:79], v[74:75]
	v_pk_mul_f32 v[72:73], v[76:77], v[72:73]
	v_mul_f32_e32 v81, 0xbfb8aa3b, v155
	v_mul_f32_e32 v80, v76, v81
	v_exp_f32_e32 v82, v80
	v_mul_f32_e32 v80, v77, v81
	v_exp_f32_e32 v83, v80
	v_mul_f32_e32 v84, v78, v81
	v_mul_f32_e32 v85, v79, v81
	v_exp_f32_e32 v84, v84
	v_exp_f32_e32 v85, v85
	v_add_f32_e32 v82, 1.0, v82
	v_add_f32_e32 v83, 1.0, v83
	v_rcp_f32_e32 v82, v82
	v_rcp_f32_e32 v83, v83
	v_add_f32_e32 v78, 1.0, v84
	v_add_f32_e32 v79, 1.0, v85
	v_rcp_f32_e32 v78, v78
	v_rcp_f32_e32 v79, v79
	v_mul_f32_e32 v80, v155, v155
	v_pk_mul_f32 v[76:77], v[80:81], v[82:83] op_sel_hi:[0,1]
	v_pk_mul_f32 v[72:73], v[72:73], v[76:77]
	v_pk_mul_f32 v[76:77], v[80:81], v[78:79] op_sel_hi:[0,1]
	v_mul_f32_e32 v78, v68, v81
	v_mul_f32_e32 v79, v69, v81
	v_exp_f32_e32 v78, v78
	v_exp_f32_e32 v79, v79
	v_pk_mul_f32 v[74:75], v[74:75], v[76:77]
	v_pk_mul_f32 v[66:67], v[70:71], v[66:67]
	v_add_f32_e32 v76, 1.0, v78
	v_add_f32_e32 v77, 1.0, v79
	v_mul_f32_e32 v78, v70, v81
	v_mul_f32_e32 v79, v71, v81
	v_exp_f32_e32 v78, v78
	v_exp_f32_e32 v79, v79
	v_rcp_f32_e32 v76, v76
	v_rcp_f32_e32 v77, v77
	v_add_f32_e32 v70, 1.0, v78
	v_add_f32_e32 v71, 1.0, v79
	v_rcp_f32_e32 v70, v70
	v_rcp_f32_e32 v71, v71
	s_or_b32 s28, s11, 3
	s_mul_hi_i32 s29, s28, 0x58
	s_mulk_i32 s28, 0x58
	s_add_u32 s28, s28, s2
	v_pk_mul_f32 v[64:65], v[68:69], v[64:65]
	v_pk_mul_f32 v[68:69], v[80:81], v[76:77] op_sel_hi:[0,1]
	s_addc_u32 s29, s29, s3
	v_pk_mul_f32 v[68:69], v[64:65], v[68:69]
	v_pk_mul_f32 v[64:65], v[80:81], v[70:71] op_sel_hi:[0,1]
	s_lshl_b64 s[28:29], s[28:29], 10
	v_pk_mul_f32 v[70:71], v[66:67], v[64:65]
	v_lshl_add_u64 v[76:77], v[134:135], 0, s[28:29]
	v_cvt_pk_bf16_f32 v64, v72, v73
	v_cvt_pk_bf16_f32 v65, v74, v75
	v_cvt_pk_bf16_f32 v66, v68, v69
	v_cvt_pk_bf16_f32 v67, v70, v71
; __device__ __forceinline__ unsigned cvtpk(float lo, float hi) { f32x2_t v = {lo, hi}; bf16x2_t b = __builtin_convertvector(v, bf16x2_t); return __builtin_bit_cast(unsigned, b); }
;     __device__ __forceinline__ void operator()(const AccT& acc, const Unit& u, int wr, int wc, int fr, int fq, LAS unsigned char* stg) const {
;     ...
;                 const float k1 = rs[ai][m] * -1.4426950408889634f, k2 = rs[ai][m] * rs[ai][m];
;                 float r[8];
; #pragma unroll
;                 for (int n = 0; n < 2; ++n)
; #pragma unroll
;                     for (int i = 0; i < 4; ++i) {
;                         const float g = acc[ai][0][m][n][i], up = acc[ai][1][m][n][i];
;                         const float e = __builtin_amdgcn_exp2f(g * k1);
;                         r[n * 4 + i] = (g * up) * (k2 * __builtin_amdgcn_rcpf(1.0f + e));
;                     }
;                 u32x4 w; w.x = cvtpk(r[0], r[1]); w.y = cvtpk(r[2], r[3]); w.z = cvtpk(r[4], r[5]); w.w = cvtpk(r[6], r[7]);
;                 __builtin_nontemporal_store(w, (u32x4*)rowp);
	global_store_dwordx4 v[76:77], v[64:67], off nt
	v_pk_mul_f32 v[58:59], v[62:63], v[58:59]
	v_pk_mul_f32 v[56:57], v[60:61], v[56:57]
	v_mul_f32_e32 v65, 0xbfb8aa3b, v152
	v_mul_f32_e32 v64, v60, v65
	v_exp_f32_e32 v66, v64
	v_mul_f32_e32 v64, v61, v65
	v_exp_f32_e32 v67, v64
	v_mul_f32_e32 v68, v62, v65
	v_mul_f32_e32 v69, v63, v65
	v_exp_f32_e32 v68, v68
	v_exp_f32_e32 v69, v69
	v_add_f32_e32 v66, 1.0, v66
	v_add_f32_e32 v67, 1.0, v67
	v_rcp_f32_e32 v66, v66
	v_rcp_f32_e32 v67, v67
	v_add_f32_e32 v62, 1.0, v68
	v_add_f32_e32 v63, 1.0, v69
	v_rcp_f32_e32 v62, v62
	v_rcp_f32_e32 v63, v63
	v_mul_f32_e32 v64, v152, v152
	v_pk_mul_f32 v[60:61], v[64:65], v[66:67] op_sel_hi:[0,1]
	v_pk_mul_f32 v[56:57], v[56:57], v[60:61]
	v_pk_mul_f32 v[60:61], v[64:65], v[62:63] op_sel_hi:[0,1]
	v_mul_f32_e32 v62, v52, v65
	v_mul_f32_e32 v63, v53, v65
	v_exp_f32_e32 v62, v62
	v_exp_f32_e32 v63, v63
	v_pk_mul_f32 v[58:59], v[58:59], v[60:61]
	v_pk_mul_f32 v[50:51], v[54:55], v[50:51]
	v_add_f32_e32 v60, 1.0, v62
	v_add_f32_e32 v61, 1.0, v63
	v_mul_f32_e32 v62, v54, v65
	v_mul_f32_e32 v63, v55, v65
	v_exp_f32_e32 v62, v62
	v_exp_f32_e32 v63, v63
	v_rcp_f32_e32 v60, v60
	v_rcp_f32_e32 v61, v61
	v_add_f32_e32 v54, 1.0, v62
	v_add_f32_e32 v55, 1.0, v63
	v_rcp_f32_e32 v54, v54
	v_rcp_f32_e32 v55, v55
	s_add_i32 s28, s11, 8
	s_mul_hi_i32 s29, s28, 0x58
	s_add_i32 s28, s13, 0x2c0
	s_add_u32 s28, s28, s2
	v_pk_mul_f32 v[48:49], v[52:53], v[48:49]
	v_pk_mul_f32 v[52:53], v[64:65], v[60:61] op_sel_hi:[0,1]
	s_addc_u32 s29, s29, s3
	v_pk_mul_f32 v[52:53], v[48:49], v[52:53]
	v_pk_mul_f32 v[48:49], v[64:65], v[54:55] op_sel_hi:[0,1]
	s_lshl_b64 s[28:29], s[28:29], 10
	v_pk_mul_f32 v[54:55], v[50:51], v[48:49]
	v_lshl_add_u64 v[60:61], v[134:135], 0, s[28:29]
	v_cvt_pk_bf16_f32 v48, v56, v57
	v_cvt_pk_bf16_f32 v49, v58, v59
	v_cvt_pk_bf16_f32 v50, v52, v53
	v_cvt_pk_bf16_f32 v51, v54, v55
	global_store_dwordx4 v[60:61], v[48:51], off nt
	v_pk_mul_f32 v[42:43], v[46:47], v[42:43]
	v_pk_mul_f32 v[40:41], v[44:45], v[40:41]
	v_mul_f32_e32 v49, 0xbfb8aa3b, v147
	v_mul_f32_e32 v48, v44, v49
	v_exp_f32_e32 v50, v48
	v_mul_f32_e32 v48, v45, v49
	v_exp_f32_e32 v51, v48
	v_mul_f32_e32 v52, v46, v49
	v_mul_f32_e32 v53, v47, v49
	v_exp_f32_e32 v52, v52
	v_exp_f32_e32 v53, v53
	v_add_f32_e32 v50, 1.0, v50
	v_add_f32_e32 v51, 1.0, v51
	v_rcp_f32_e32 v50, v50
	v_rcp_f32_e32 v51, v51
	v_add_f32_e32 v46, 1.0, v52
	v_add_f32_e32 v47, 1.0, v53
	v_rcp_f32_e32 v46, v46
	v_rcp_f32_e32 v47, v47
	v_mul_f32_e32 v48, v147, v147
	v_pk_mul_f32 v[44:45], v[48:49], v[50:51] op_sel_hi:[0,1]
	v_pk_mul_f32 v[40:41], v[40:41], v[44:45]
	v_pk_mul_f32 v[44:45], v[48:49], v[46:47] op_sel_hi:[0,1]
	v_mul_f32_e32 v46, v36, v49
	v_mul_f32_e32 v47, v37, v49
	v_exp_f32_e32 v46, v46
	v_exp_f32_e32 v47, v47
	v_pk_mul_f32 v[42:43], v[42:43], v[44:45]
	v_pk_mul_f32 v[34:35], v[38:39], v[34:35]
	v_add_f32_e32 v44, 1.0, v46
	v_add_f32_e32 v45, 1.0, v47
	v_mul_f32_e32 v46, v38, v49
	v_mul_f32_e32 v47, v39, v49
	v_exp_f32_e32 v46, v46
	v_exp_f32_e32 v47, v47
	v_rcp_f32_e32 v44, v44
	v_rcp_f32_e32 v45, v45
	v_add_f32_e32 v38, 1.0, v46
	v_add_f32_e32 v39, 1.0, v47
	v_rcp_f32_e32 v38, v38
	v_rcp_f32_e32 v39, v39
	s_add_i32 s28, s11, 9
	s_mul_hi_i32 s29, s28, 0x58
	s_add_i32 s28, s13, 0x318
	s_add_u32 s28, s28, s2
	v_pk_mul_f32 v[32:33], v[36:37], v[32:33]
	v_pk_mul_f32 v[36:37], v[48:49], v[44:45] op_sel_hi:[0,1]
	s_addc_u32 s29, s29, s3
	v_pk_mul_f32 v[36:37], v[32:33], v[36:37]
	v_pk_mul_f32 v[32:33], v[48:49], v[38:39] op_sel_hi:[0,1]
	s_lshl_b64 s[28:29], s[28:29], 10
	v_pk_mul_f32 v[38:39], v[34:35], v[32:33]
	v_lshl_add_u64 v[44:45], v[134:135], 0, s[28:29]
	v_cvt_pk_bf16_f32 v32, v40, v41
	v_cvt_pk_bf16_f32 v33, v42, v43
	v_cvt_pk_bf16_f32 v34, v36, v37
	v_cvt_pk_bf16_f32 v35, v38, v39
	global_store_dwordx4 v[44:45], v[32:35], off nt
	v_pk_mul_f32 v[26:27], v[30:31], v[26:27]
; __device__ __forceinline__ unsigned cvtpk(float lo, float hi) { f32x2_t v = {lo, hi}; bf16x2_t b = __builtin_convertvector(v, bf16x2_t); return __builtin_bit_cast(unsigned, b); }
; #define PG8_BAR __builtin_amdgcn_s_barrier()
;     __device__ __forceinline__ void operator()(const AccT& acc, const Unit& u, int wr, int wc, int fr, int fq, LAS unsigned char* stg) const {
;     ...
;                 const float k1 = rs[ai][m] * -1.4426950408889634f, k2 = rs[ai][m] * rs[ai][m];
;                 float r[8];
; #pragma unroll
;                 for (int n = 0; n < 2; ++n)
; #pragma unroll
;                     for (int i = 0; i < 4; ++i) {
;                         const float g = acc[ai][0][m][n][i], up = acc[ai][1][m][n][i];
;                         const float e = __builtin_amdgcn_exp2f(g * k1);
;                         r[n * 4 + i] = (g * up) * (k2 * __builtin_amdgcn_rcpf(1.0f + e));
;                     }
;                 u32x4 w; w.x = cvtpk(r[0], r[1]); w.y = cvtpk(r[2], r[3]); w.z = cvtpk(r[4], r[5]); w.w = cvtpk(r[6], r[7]);
;                 __builtin_nontemporal_store(w, (u32x4*)rowp);
; template <class Epi>
; __device__ __forceinline__ void gemm_phase(LAS unsigned char* lds, const Gemm g, const StaticOrder& S, const Epi& E, const int tid) {
;     ...
;         if (!has_next) break;
; #pragma unroll
;         for (int a = 0; a < 2; ++a)
; #pragma unroll
;             for (int b = 0; b < 2; ++b)
; #pragma unroll
;                 for (int m = 0; m < 4; ++m)
; #pragma unroll
;                     for (int n = 0; n < 2; ++n) acc[a][b][m][n] = (f32x4){0.f, 0.f, 0.f, 0.f};
;         cur = nxt; cA = nA; cB = nB; ++ui;
;         if (wr == 1) PG8_BAR;
	v_pk_mul_f32 v[24:25], v[28:29], v[24:25]
	v_mul_f32_e32 v33, 0xbfb8aa3b, v146
	v_mul_f32_e32 v32, v28, v33
	v_exp_f32_e32 v34, v32
	v_mul_f32_e32 v32, v29, v33
	v_exp_f32_e32 v35, v32
	v_mul_f32_e32 v36, v30, v33
	v_mul_f32_e32 v37, v31, v33
	v_exp_f32_e32 v36, v36
	v_exp_f32_e32 v37, v37
	v_add_f32_e32 v34, 1.0, v34
	v_add_f32_e32 v35, 1.0, v35
	v_rcp_f32_e32 v34, v34
	v_rcp_f32_e32 v35, v35
	v_add_f32_e32 v30, 1.0, v36
	v_add_f32_e32 v31, 1.0, v37
	v_rcp_f32_e32 v30, v30
	v_rcp_f32_e32 v31, v31
	v_mul_f32_e32 v32, v146, v146
	v_pk_mul_f32 v[28:29], v[32:33], v[34:35] op_sel_hi:[0,1]
	v_pk_mul_f32 v[24:25], v[24:25], v[28:29]
	v_pk_mul_f32 v[28:29], v[32:33], v[30:31] op_sel_hi:[0,1]
	v_mul_f32_e32 v30, v20, v33
	v_mul_f32_e32 v31, v21, v33
	v_exp_f32_e32 v30, v30
	v_exp_f32_e32 v31, v31
	v_pk_mul_f32 v[26:27], v[26:27], v[28:29]
	v_pk_mul_f32 v[18:19], v[22:23], v[18:19]
	v_add_f32_e32 v28, 1.0, v30
	v_add_f32_e32 v29, 1.0, v31
	v_mul_f32_e32 v30, v22, v33
	v_mul_f32_e32 v31, v23, v33
	v_exp_f32_e32 v30, v30
	v_exp_f32_e32 v31, v31
	v_rcp_f32_e32 v28, v28
	v_rcp_f32_e32 v29, v29
	v_add_f32_e32 v22, 1.0, v30
	v_add_f32_e32 v23, 1.0, v31
	v_rcp_f32_e32 v22, v22
	v_rcp_f32_e32 v23, v23
	s_add_i32 s28, s11, 10
	s_mul_hi_i32 s29, s28, 0x58
	s_add_i32 s28, s13, 0x370
	s_add_u32 s28, s28, s2
	v_pk_mul_f32 v[16:17], v[20:21], v[16:17]
	v_pk_mul_f32 v[20:21], v[32:33], v[28:29] op_sel_hi:[0,1]
	s_addc_u32 s29, s29, s3
	v_pk_mul_f32 v[20:21], v[16:17], v[20:21]
	v_pk_mul_f32 v[16:17], v[32:33], v[22:23] op_sel_hi:[0,1]
	s_lshl_b64 s[28:29], s[28:29], 10
	v_pk_mul_f32 v[22:23], v[18:19], v[16:17]
	v_lshl_add_u64 v[28:29], v[134:135], 0, s[28:29]
	v_cvt_pk_bf16_f32 v16, v24, v25
	v_cvt_pk_bf16_f32 v17, v26, v27
	v_cvt_pk_bf16_f32 v18, v20, v21
	v_cvt_pk_bf16_f32 v19, v22, v23
	global_store_dwordx4 v[28:29], v[16:19], off nt
	v_pk_mul_f32 v[10:11], v[14:15], v[10:11]
	v_pk_mul_f32 v[8:9], v[12:13], v[8:9]
	v_mul_f32_e32 v17, 0xbfb8aa3b, v145
	v_mul_f32_e32 v16, v12, v17
	v_exp_f32_e32 v18, v16
	v_mul_f32_e32 v16, v13, v17
	v_exp_f32_e32 v19, v16
	v_mul_f32_e32 v20, v14, v17
	v_mul_f32_e32 v21, v15, v17
	v_exp_f32_e32 v20, v20
	v_exp_f32_e32 v21, v21
	v_add_f32_e32 v18, 1.0, v18
	v_add_f32_e32 v19, 1.0, v19
	v_rcp_f32_e32 v18, v18
	v_rcp_f32_e32 v19, v19
	v_add_f32_e32 v14, 1.0, v20
	v_add_f32_e32 v15, 1.0, v21
	v_rcp_f32_e32 v14, v14
	v_rcp_f32_e32 v15, v15
	v_mul_f32_e32 v16, v145, v145
	v_pk_mul_f32 v[12:13], v[16:17], v[18:19] op_sel_hi:[0,1]
	v_pk_mul_f32 v[8:9], v[8:9], v[12:13]
	v_pk_mul_f32 v[12:13], v[16:17], v[14:15] op_sel_hi:[0,1]
	v_mul_f32_e32 v14, v4, v17
	v_mul_f32_e32 v15, v5, v17
	v_exp_f32_e32 v14, v14
	v_exp_f32_e32 v15, v15
	v_pk_mul_f32 v[10:11], v[10:11], v[12:13]
	v_pk_mul_f32 v[2:3], v[6:7], v[2:3]
	v_add_f32_e32 v12, 1.0, v14
	v_add_f32_e32 v13, 1.0, v15
	v_mul_f32_e32 v14, v6, v17
	v_mul_f32_e32 v15, v7, v17
	v_exp_f32_e32 v14, v14
	v_exp_f32_e32 v15, v15
	v_rcp_f32_e32 v12, v12
	v_rcp_f32_e32 v13, v13
	v_add_f32_e32 v6, 1.0, v14
	v_add_f32_e32 v7, 1.0, v15
	v_rcp_f32_e32 v6, v6
	v_rcp_f32_e32 v7, v7
	s_add_i32 s11, s11, 11
	s_addk_i32 s13, 0x3c8
	s_mul_hi_i32 s11, s11, 0x58
	s_add_u32 s2, s13, s2
	v_pk_mul_f32 v[0:1], v[4:5], v[0:1]
	v_pk_mul_f32 v[4:5], v[16:17], v[12:13] op_sel_hi:[0,1]
	s_addc_u32 s3, s11, s3
	v_pk_mul_f32 v[4:5], v[0:1], v[4:5]
	v_pk_mul_f32 v[0:1], v[16:17], v[6:7] op_sel_hi:[0,1]
	s_lshl_b64 s[2:3], s[2:3], 10
	v_pk_mul_f32 v[6:7], v[2:3], v[0:1]
	v_lshl_add_u64 v[12:13], v[134:135], 0, s[2:3]
	v_cvt_pk_bf16_f32 v0, v8, v9
	v_cvt_pk_bf16_f32 v1, v10, v11
	v_cvt_pk_bf16_f32 v2, v4, v5
	v_cvt_pk_bf16_f32 v3, v6, v7
	s_andn2_b64 vcc, exec, s[4:5]
	s_mov_b64 s[2:3], -1
	global_store_dwordx4 v[12:13], v[0:3], off nt
	s_cbranch_vccnz .LBB0_449
	s_andn2_b64 vcc, exec, s[6:7]
	s_cbranch_vccnz .LBB0_448
	s_barrier
	s_branch .LBB0_448
